# scan step top: the two staged output-row LDS reads issued together (one exposed LDS round trip instead of two per step); on top of prep6
# baseline (speedup 1.0000x reference)
.LBB0_568:
	s_andn2_b32 s6, 0x4000, s19
	v_add_u32_e32 v38, s6, v102
	s_lshl_b32 s6, s27, 6
	v_add_u32_e32 v32, v38, v83
	v_add_u32_e32 v40, v38, v81
	s_add_i32 s6, s6, s18
	ds_read_b128 v[32:35], v32
	ds_read_b128 v[40:43], v40
	v_add_u32_e32 v36, s6, v82
	v_ashrrev_i32_e32 v37, 31, v36
	v_lshlrev_b64 v[36:37], 11, v[36:37]
	v_lshl_add_u64 v[36:37], v[64:65], 0, v[36:37]
	v_add_u32_e32 v44, s6, v69
	v_ashrrev_i32_e32 v45, 31, v44
	v_lshlrev_b64 v[44:45], 11, v[44:45]
	v_lshl_add_u64 v[44:45], v[64:65], 0, v[44:45]
	s_waitcnt lgkmcnt(1)
	global_store_dwordx4 v[36:37], v[32:35], off nt
	s_waitcnt lgkmcnt(0)
	global_store_dwordx4 v[44:45], v[40:43], off nt
